# QKV GEMM unit order: column tiles permuted [0,1,4,5,2,3] so the store-heavy K/V tiles run on the workgroups that own a single unit; Q tiles pair up
# speedup vs baseline: 1.0081x; 1.0019x over previous
.LBB0_303:
	s_ashr_i32 s6, s82, 31
	s_lshr_b32 s6, s6, 29
	s_add_i32 s6, s82, s6
	s_ashr_i32 s7, s6, 3
	s_and_b32 s6, s6, -8
	s_sub_i32 s6, s82, s6
	s_cmp_lt_i32 s6, 0
	s_cselect_b32 s13, 49, 48
	s_mul_i32 s6, s6, s13
	s_add_i32 s6, s6, s7
	s_mul_hi_i32 s7, s6, 0x2aaaaaab
	s_lshr_b32 s13, s7, 31
	s_ashr_i32 s7, s7, 3
	s_add_i32 s7, s7, s13
	s_lshl_b32 s13, s7, 3
	s_mul_i32 s7, s7, 48
	s_sub_i32 s6, s6, s7
	s_bfe_i32 s7, s6, 0x80000
	s_bfe_u32 s7, s7, 0x3000c
	s_add_i32 s7, s6, s7
	s_bfe_i32 s14, s7, 0x80000
	s_and_b32 s7, s7, 0xf8
	s_sub_i32 s6, s6, s7
	s_sext_i32_i16 s14, s14
	s_sext_i32_i8 s6, s6
	s_add_i32 s70, s13, s6
	s_ashr_i32 s26, s14, 3
	s_cmp_ge_u32 s26, 2
	s_cselect_b32 s7, 6, 0
	s_xor_b32 s26, s26, s7
	s_lshr_b32 s83, s36, 1
	s_andn2_b64 vcc, exec, s[4:5]
	s_mul_i32 s13, s83, 0x500000
	s_cbranch_vccnz .LBB0_301

.LBB0_309:
	s_add_i32 s34, s34, 1
	s_mul_i32 s2, s34, s57
	s_mul_hi_u32 s3, s34, s10
	s_add_i32 s3, s3, s2
	s_mul_i32 s2, s34, s10
	s_add_u32 s22, s2, s82
	s_addc_u32 s23, s3, s97
	v_mov_b64_e32 v[0:1], 0x180
	v_cmp_lt_i64_e64 s[2:3], s[22:23], v[0:1]
	v_mov_b64_e32 v[0:1], 0x17f
	v_cmp_gt_i64_e32 vcc, s[22:23], v[0:1]
	s_cbranch_vccnz .LBB0_311
	s_ashr_i32 s18, s22, 31
	s_lshr_b32 s18, s18, 29
	s_add_i32 s18, s22, s18
	s_ashr_i32 s19, s18, 3
	s_and_b32 s18, s18, -8
	s_sub_i32 s18, s22, s18
	s_cmp_lt_i32 s18, 0
	s_cselect_b32 s20, 49, 48
	s_mul_i32 s18, s18, s20
	s_add_i32 s18, s18, s19
	s_mul_hi_i32 s19, s18, 0x2aaaaaab
	s_lshr_b32 s20, s19, 31
	s_ashr_i32 s19, s19, 3
	s_add_i32 s19, s19, s20
	s_lshl_b32 s20, s19, 3
	s_sub_i32 s21, 64, s20
	s_min_i32 s21, s21, 8
	s_abs_i32 s22, s21
	v_cvt_f32_u32_e32 v0, s22
	s_sub_i32 s24, 0, s22
	s_mul_i32 s19, s19, 48
	s_sub_i32 s19, s18, s19
	v_rcp_iflag_f32_e32 v0, v0
	s_abs_i32 s18, s19
	s_xor_b32 s23, s19, s21
	s_ashr_i32 s23, s23, 31
	v_mul_f32_e32 v0, 0x4f7ffffe, v0
	v_cvt_u32_f32_e32 v0, v0
	s_nop 0
	v_readfirstlane_b32 s25, v0
	s_mul_i32 s24, s24, s25
	s_mul_hi_u32 s24, s25, s24
	s_add_i32 s25, s25, s24
	s_mul_hi_u32 s24, s18, s25
	s_mul_i32 s25, s24, s22
	s_sub_i32 s18, s18, s25
	s_add_i32 s30, s24, 1
	s_sub_i32 s25, s18, s22
	s_cmp_ge_u32 s18, s22
	s_cselect_b32 s24, s30, s24
	s_cselect_b32 s18, s25, s18
	s_add_i32 s25, s24, 1
	s_cmp_ge_u32 s18, s22
	s_cselect_b32 s18, s25, s24
	s_xor_b32 s18, s18, s23
	s_sub_i32 s18, s18, s23
	s_mul_i32 s21, s18, s21
	s_sub_i32 s19, s19, s21
	s_add_i32 s20, s20, s19
	s_cmp_ge_u32 s18, 2
	s_cselect_b32 s19, 6, 0
	s_xor_b32 s18, s18, s19
